# static priority raise for waves 0-3 also in the stick-breaking attention phase
# baseline (speedup 1.0000x reference)
; #define LAS __attribute__((address_space(3)))
; __device__ __forceinline__ void sb_unit(LAS unsigned char* lds, int bh, int qb, const bf16* Q, const bf16* K, const bf16* VT, bf16* OUT, ssq_t* SSo, int tid, int lane, int wave) {
;     const int r32 = lane & 31, hi = lane >> 5;
;     LAS bf16* Ks = (LAS bf16*)lds;
;     LAS bf16* Vs = Ks + 64 * 72;
;     LAS unsigned* flags = (LAS unsigned*)(lds + 2 * 64 * 72 * 2);
;     const int q0 = qb * 256, qg = q0 + 32 * wave + r32;
;     const bf16* Qp = Q + ((size_t)bh * S + qg) * 64;
;     bf16x8 qr[4];
; #pragma unroll
;     for (int d0 = 0; d0 < 4; ++d0) qr[d0] = *(const bf16x8*)(Qp + 16 * d0 + 8 * hi);
;     f16x8 tri0, tri1, ones;
; #pragma unroll
;     for (int j = 0; j < 8; ++j) { const int k0 = 8 * (j >> 2) + 4 * hi + (j & 3);
;         tri0[j] = (k0 >= r32) ? (_Float16)1.0f : (_Float16)0.0f; tri1[j] = (16 + k0 >= r32) ? (_Float16)1.0f : (_Float16)0.0f; ones[j] = (_Float16)1.0f; }
;     f32x16 o0, o1;
; #pragma unroll
;     for (int r = 0; r < 16; ++r) { o0[r] = 0.f; o1[r] = 0.f; }
;     float C = 0.f;
;     const bf16* Kb = K + (size_t)bh * S * 64;
;     const bf16* Vb = VT + (size_t)bh * 64 * S;
;     const int lrow = tid >> 3, lch = tid & 7;
;     u32x4 kv = *(const u32x4*)(Kb + (size_t)(64 * (4 * qb + 3) + lrow) * 64 + lch * 8);
;     u32x4 vv = *(const u32x4*)(Vb + (size_t)lrow * S + 64 * (4 * qb + 3) + lch * 8);
; __global__ void __launch_bounds__(512, 2) hybrid_fwd(Args args) {
;     ...
;         for (int i = vcu2; i < 512; i += G) { const int round = i >> 8, v = i & 255, bh = v >> 4, s = v & 15, qb = round == 0 ? 31 - s : s; sb_unit(lds, bh, qb, SBQ, SBK, SBVT, MIXRAW, SSP(layer * 8 + 6), tid, lane, wave); __syncthreads(); } }
.LBB0_1268:
	s_or_b64 exec, exec, s[2:3]
	v_readlane_b32 s1, v255, 27
	s_cmpk_lt_i32 s1, 0x200
	s_cselect_b64 s[6:7], -1, 0
	v_writelane_b32 v255, s6, 52
	s_waitcnt lgkmcnt(0)
	v_mov_b32_e32 v2, v194
	s_mov_b64 s[2:3], 0
	v_writelane_b32 v255, s7, 53
	s_cmpk_gt_i32 s1, 0x1ff
	s_barrier
	s_cbranch_scc1 .LBB0_1281
	v_bfe_u32 v5, v2, 5, 1
	v_readlane_b32 s6, v252, 7
	v_and_b32_e32 v1, 31, v2
	v_lshlrev_b32_e32 v132, 2, v5
	v_readlane_b32 s7, v252, 8
	s_add_u32 s6, s6, s2
	v_cmp_lt_u32_e32 vcc, v132, v1
	v_or_b32_e32 v7, 16, v132
	s_addc_u32 s7, s7, s3
	v_cndmask_b32_e64 v6, v205, 0, vcc
	v_cmp_lt_u32_e32 vcc, v7, v1
	v_or_b32_e32 v9, 1, v132
	s_add_u32 s16, s6, 0x5500000
	v_cndmask_b32_e64 v7, v205, 0, vcc
	v_or_b32_e32 v8, 2, v132
	v_cmp_lt_u32_e32 vcc, v9, v1
	s_addc_u32 s17, s7, 0
	v_or_b32_e32 v11, 17, v132
	v_cndmask_b32_e64 v9, v205, 0, vcc
	v_cmp_lt_u32_e32 vcc, v8, v1
	s_add_u32 s4, s6, 0x6500000
	v_or_b32_e32 v10, 18, v132
	v_cndmask_b32_e64 v8, v205, 0, vcc
	v_cmp_lt_u32_e32 vcc, v11, v1
	s_addc_u32 s22, s7, 0
	v_readlane_b32 s8, v255, 46
	v_cndmask_b32_e64 v11, v205, 0, vcc
	v_cmp_lt_u32_e32 vcc, v10, v1
	v_or_b32_e32 v13, 3, v132
	s_add_u32 s36, s6, 0xc500000
	v_readlane_b32 s9, v255, 47
	v_cndmask_b32_e64 v10, v205, 0, vcc
	v_cmp_lt_u32_e32 vcc, v13, v1
	v_ashrrev_i32_e32 v134, 3, v2
	s_addc_u32 s37, s7, 0
	s_lshl_b64 s[8:9], s[8:9], 3
	v_or_b32_e32 v12, 8, v132
	v_cndmask_b32_e64 v13, v205, 0, vcc
	v_ashrrev_i32_e32 v135, 31, v134
	s_add_u32 s8, s6, s8
	v_cmp_lt_u32_e32 vcc, v12, v1
	v_or_b32_e32 v15, 19, v132
	v_pack_b32_f16 v101, v8, v13
	v_pack_b32_f16 v100, v6, v9
	v_lshlrev_b32_e32 v6, 3, v2
	v_lshlrev_b64 v[8:9], 14, v[134:135]
	s_addc_u32 s9, s7, s9
	v_cndmask_b32_e64 v12, v205, 0, vcc
	v_or_b32_e32 v14, 24, v132
	v_cmp_lt_u32_e32 vcc, v15, v1
	v_and_b32_e32 v6, 56, v6
	v_lshl_add_u64 v[8:9], s[6:7], 0, v[8:9]
	s_mov_b64 s[6:7], 0x7500000
	s_movk_i32 s1, 0x90
	v_cndmask_b32_e64 v15, v205, 0, vcc
	v_cmp_lt_u32_e32 vcc, v14, v1
	v_or_b32_e32 v16, 10, v132
	v_pack_b32_f16 v104, v7, v11
	v_lshl_add_u64 v[136:137], v[8:9], 0, s[6:7]
	v_lshlrev_b32_e32 v7, 1, v6
	v_mul_lo_u32 v8, v134, s1
	v_and_b32_e32 v3, 63, v2
	v_lshlrev_b32_e32 v4, 3, v5
	v_cndmask_b32_e64 v14, v205, 0, vcc
	v_or_b32_e32 v17, 9, v132
	v_cmp_lt_u32_e32 vcc, v16, v1
	v_add3_u32 v133, 0, v7, v8
	v_mul_u32_u24_e32 v7, 0x90, v1
	v_lshlrev_b32_e32 v5, 4, v5
	v_cndmask_b32_e64 v16, v205, 0, vcc
	v_cmp_lt_u32_e32 vcc, v17, v1
	v_or_b32_e32 v18, 26, v132
	v_add3_u32 v135, 0, v7, v5
	v_or_b32_e32 v7, 32, v3
	v_cndmask_b32_e64 v17, v205, 0, vcc
	v_or_b32_e32 v19, 25, v132
	v_cmp_lt_u32_e32 vcc, v18, v1
	v_mul_u32_u24_e32 v8, 0x90, v7
	s_add_u32 s30, s8, 0x105d0000
	v_cndmask_b32_e64 v18, v205, 0, vcc
	v_cmp_lt_u32_e32 vcc, v19, v1
	v_or_b32_e32 v20, 11, v132
	v_add3_u32 v148, 0, v8, v5
	v_add_u32_e32 v5, 0, v4
	s_addc_u32 s28, s9, 0
	v_cndmask_b32_e64 v19, v205, 0, vcc
	v_cmp_lt_u32_e32 vcc, v20, v1
	v_or_b32_e32 v21, 27, v132
	v_mad_u32_u24 v149, v1, s1, v5
	v_mad_u32_u24 v151, v7, s1, v5
	v_readlane_b32 s1, v255, 7
	v_cndmask_b32_e64 v20, v205, 0, vcc
	v_cmp_lt_u32_e32 vcc, v21, v1
	v_and_b32_e32 v2, 7, v2
	s_add_u32 s2, s1, s2
	v_readlane_b32 s1, v255, 8
	v_cndmask_b32_e64 v21, v205, 0, vcc
	v_lshlrev_b32_e32 v98, 4, v2
	s_addc_u32 s3, s1, s3
	v_pack_b32_f16 v102, v12, v17
	v_pack_b32_f16 v103, v16, v20
	v_pack_b32_f16 v106, v14, v19
	v_pack_b32_f16 v105, v10, v15
	v_pack_b32_f16 v107, v18, v21
	v_cmp_eq_u32_e64 s[42:43], 0, v3
	v_add_u32_e32 v150, 0x2410, v149
	v_add_u32_e32 v152, 0x2410, v151
	v_cmp_gt_u32_e64 s[44:45], 32, v3
	v_lshl_add_u64 v[138:139], s[2:3], 0, v[98:99]
	v_add_u32_e32 v153, 0x80, v134
	v_lshlrev_b32_e32 v140, 1, v4
	v_lshlrev_b32_e32 v142, 1, v6
	v_readfirstlane_b32 s32, v194
	s_cmpk_ge_u32 s32, 0x100
	s_cbranch_scc1 .Lsb_prio_skip
	s_setprio 1
.Lsb_prio_skip:
	v_readlane_b32 s31, v255, 27
	s_branch .LBB0_1271

; #define LAS __attribute__((address_space(3)))
; #define PHASE() size_t z_ = 0; asm volatile("" : "+s"(z_)); unsigned char* ws = args.ws + z_; float* H = args.out + z_; (void)H; (void)ws;
; #define RELANE() int tid = threadIdx.x; asm volatile("" : "+v"(tid)); const int lane = tid & 63; (void)lane;
; __device__ __forceinline__ void mla_unit(LAS unsigned char* lds, int bh, int x, const bf16* QM, const bf16* KM, const bf16* VMT, bf16* OUT, ssq_t* SSo, int tid, int lane, int wave) {
;     const int r32 = lane & 31, hi = lane >> 5, g = wave >> 2, wq = wave & 3;
;     const int q0 = 128 * x, qg = q0 + 32 * wq + r32, T = 2 * (x + 1);
;     LAS bf16* L = (LAS bf16*)lds;
;     LAS bf16* Qs = L + MLA_QOFF;
;     const LAS bf16* Qw = Qs + (32 * wq + r32) * 200 + 8 * hi;
;     const LAS bf16* Kw = L + MLA_KOFF + g * MLA_KS + r32 * 200 + 8 * hi;
;     const LAS bf16* Vw = L + MLA_VOFF + g * MLA_VS + r32 * 36 + 4 * hi;
;     f32x16 o[4];
; #pragma unroll
;     for (int k = 0; k < 4; ++k)
; #pragma unroll
;         for (int r = 0; r < 16; ++r) o[k][r] = 0.f;
;     float mref = 0.f, lrun = 0.f;
;     const bf16* Kb = KM + (size_t)bh * S * 192;
;     const bf16* Vb = VMT + (size_t)bh * 128 * S;
;     u32x4 rk0[3], rv0[2], rk1[3], rv1[2];
;     const unsigned kgo = (unsigned)tid * 16u;
;     const unsigned vgo = (unsigned)((tid >> 3) * S + (tid & 7) * 8) * 2u;
;     unsigned kds[3];
; #pragma unroll
;     for (int i = 0; i < 3; ++i) { const int c = tid + 512 * i, row = c / 24, ch = c - 24 * row; kds[i] = (unsigned)(MLA_KOFF + (row >> 5) * MLA_KS + (row & 31) * 200 + ch * 8); }
;     const unsigned vds = (unsigned)(MLA_VOFF + ((tid & 7) >> 2) * MLA_VS + (tid >> 3) * 36 + (tid & 3) * 8);
; __global__ void __launch_bounds__(512, 2) hybrid_fwd(Args args) {
;     ...
;         { RELANE(); PHASE();
;         for (int i = vcu2; i < 512; i += G) { const int round = i >> 8, v = i & 255, bh = v >> 5, s = v & 31, x = round == 0 ? 63 - s : s; mla_unit(lds, bh, x, QM, KM, VMT, MIXRAW, SSP(layer * 8 + 7), tid, lane, wave); } }
.LBB0_1281:
	s_setprio 0
	v_readlane_b32 s6, v255, 52
	v_readlane_b32 s7, v255, 53
	v_mov_b32_e32 v2, v194
	s_mov_b64 s[2:3], 0
	s_andn2_b64 vcc, exec, s[6:7]
	s_cbranch_vccnz .LBB0_1320
	v_readlane_b32 s10, v252, 7
	v_readlane_b32 s11, v252, 8
	s_add_u32 s6, s10, s2
	s_addc_u32 s7, s11, s3
	s_add_u32 s13, s6, 0x8500000
	s_addc_u32 s34, s7, 0
	v_readlane_b32 s8, v255, 46
	s_add_u32 s35, s6, 0x9d00000
	v_readlane_b32 s9, v255, 47
	s_addc_u32 s36, s7, 0
	s_lshl_b64 s[8:9], s[8:9], 3
	s_add_u32 s4, s6, s8
	s_addc_u32 s8, s7, s9
	v_and_b32_e32 v3, 31, v2
	v_bfe_u32 v4, v2, 5, 1
	v_readlane_b32 s1, v253, 48
	s_add_u32 s37, s4, 0x105f0000
	v_lshlrev_b32_e32 v15, 3, v4
	v_or_b32_e32 v165, s1, v3
	v_mul_u32_u24_e32 v7, 0x190, v3
	v_mul_u32_u24_e32 v16, 0x48, v3
	v_lshlrev_b32_e32 v164, 2, v4
	v_lshlrev_b32_e32 v3, 4, v4
	v_and_b32_e32 v4, 7, v2
	s_mov_b32 s14, 0x2aaaaaab
	s_addc_u32 s40, s8, 0
	v_mul_u32_u24_e32 v5, 0x190, v165
	s_add_i32 s4, 0, 0x1a000
	v_lshlrev_b32_e32 v18, 4, v4
	v_mul_hi_i32 v4, v2, s14
	v_add3_u32 v208, s4, v5, v3
	v_lshrrev_b32_e32 v5, 31, v4
	v_ashrrev_i32_e32 v4, 2, v4
	v_add_u32_e32 v11, v4, v5
	s_movk_i32 s15, 0xffe8
	v_mad_u64_u32 v[4:5], s[8:9], v11, s15, v[2:3]
	v_lshrrev_b32_e32 v5, 5, v11
	v_and_b32_e32 v6, 31, v11
	v_mul_i32_i24_e32 v5, 0x1900, v5
	v_mul_u32_u24_e32 v6, 0xc8, v6
	v_lshlrev_b32_e32 v8, 3, v4
	v_add3_u32 v19, v5, v6, v8
	v_add_u32_e32 v6, 0x200, v2
	v_mul_hi_i32 v5, v6, s14
	v_lshrrev_b32_e32 v8, 31, v5
	v_ashrrev_i32_e32 v5, 2, v5
	v_add_u32_e32 v5, v5, v8
	v_mad_u64_u32 v[8:9], s[8:9], v5, s15, v[6:7]
	v_lshrrev_b32_e32 v9, 5, v5
	v_and_b32_e32 v10, 31, v5
	v_mul_i32_i24_e32 v9, 0x1900, v9
	v_mul_u32_u24_e32 v10, 0xc8, v10
	v_lshlrev_b32_e32 v12, 3, v8
	v_add3_u32 v9, v9, v10, v12
	v_add_u32_e32 v10, 0x400, v2
	v_mul_hi_i32 v12, v10, s14
	v_lshrrev_b32_e32 v13, 31, v12
	v_ashrrev_i32_e32 v12, 2, v12
	v_add_u32_e32 v20, v12, v13
	v_mad_u64_u32 v[12:13], s[8:9], v20, s15, v[10:11]
	v_lshrrev_b32_e32 v13, 5, v20
	v_and_b32_e32 v14, 31, v20
	v_readlane_b32 s1, v253, 46
	v_mul_i32_i24_e32 v13, 0x1900, v13
	v_mul_u32_u24_e32 v14, 0xc8, v14
	v_lshlrev_b32_e32 v21, 3, v12
	v_add3_u32 v209, s1, v7, v3
	v_lshlrev_b32_e32 v3, 3, v2
	v_add3_u32 v13, v13, v14, v21
	v_and_b32_e32 v14, 24, v3
	v_ashrrev_i32_e32 v3, 31, v2
	s_movk_i32 s1, 0x190
	v_lshlrev_b64 v[166:167], 4, v[2:3]
	v_mul_lo_u32 v3, v11, s1
	v_add_u32_e32 v22, s4, v3
	v_ashrrev_i32_e32 v7, 31, v6
	v_mul_lo_u32 v3, v5, s1
	v_lshlrev_b32_e32 v23, 4, v4
	v_lshlrev_b64 v[168:169], 4, v[6:7]
	v_add_u32_e32 v6, s4, v3
	v_mul_lo_u32 v3, v20, s1
	v_add_u32_e32 v4, 0x600, v2
	v_lshlrev_b32_e32 v7, 4, v8
	v_add_u32_e32 v8, s4, v3
	v_mul_hi_i32 v3, v4, s14
	v_lshrrev_b32_e32 v5, 31, v3
	v_ashrrev_i32_e32 v3, 2, v3
	v_ashrrev_i32_e32 v11, 31, v10
	v_add_u32_e32 v3, v3, v5
	v_lshlrev_b64 v[170:171], 4, v[10:11]
	v_mul_lo_u32 v11, v3, s15
	v_ashrrev_i32_e32 v5, 31, v4
	v_lshlrev_b64 v[172:173], 4, v[4:5]
	v_mul_lo_u32 v3, v3, s1
	v_add_lshl_u32 v11, v11, v4, 4
	v_add_u32_e32 v4, 0x800, v2
	v_lshlrev_b32_e32 v10, 4, v12
	v_add_u32_e32 v12, s4, v3
	v_mul_hi_i32 v3, v4, s14
	v_lshrrev_b32_e32 v5, 31, v3
	v_ashrrev_i32_e32 v3, 2, v3
	v_add_u32_e32 v3, v3, v5
	v_mul_lo_u32 v20, v3, s15
	v_ashrrev_i32_e32 v5, 31, v4
	v_lshlrev_b64 v[174:175], 4, v[4:5]
	v_mul_lo_u32 v3, v3, s1
	v_add_lshl_u32 v20, v20, v4, 4
	v_add_u32_e32 v4, 0xa00, v2
	v_add_u32_e32 v24, s4, v3
	v_mul_hi_i32 v3, v4, s14
	v_lshrrev_b32_e32 v5, 31, v3
	v_ashrrev_i32_e32 v3, 2, v3
	v_add_u32_e32 v3, v3, v5
	v_ashrrev_i32_e32 v17, 3, v2
	v_bfe_u32 v21, v2, 2, 1
	v_mul_lo_u32 v25, v3, s15
	v_ashrrev_i32_e32 v5, 31, v4
	v_mul_lo_u32 v3, v3, s1
	v_and_b32_e32 v1, 63, v2
	v_lshlrev_b64 v[176:177], 4, v[4:5]
	v_add_u32_e32 v5, s4, v3
	v_lshlrev_b32_e32 v178, 4, v2
	v_mul_u32_u24_e32 v21, 0x1200, v21
	v_readlane_b32 s1, v253, 47
	v_mad_u64_u32 v[2:3], s[8:9], v17, 36, v[14:15]
	s_nop 0
	v_add3_u32 v210, s1, v16, v15
	v_add_lshl_u32 v2, v2, v21, 1
	v_readlane_b32 s1, v255, 26
	v_lshl_or_b32 v98, v17, 14, v18
	v_add_u32_e32 v214, 0, v2
	v_add_u32_e32 v2, s1, v2
	v_add_lshl_u32 v4, v25, v4, 4
	v_mov_b32_e32 v179, v99
	v_add_u32_e32 v215, 0xc800, v2
	v_readlane_b32 s1, v253, 49
	v_lshl_add_u64 v[2:3], s[6:7], 0, v[98:99]
	s_mov_b64 s[8:9], 0xb500000
	v_lshl_add_u32 v211, v19, 1, 0
	v_lshl_add_u32 v212, v9, 1, 0
	v_lshl_add_u32 v213, v13, 1, 0
	v_lshl_add_u32 v216, v1, 2, s1
	v_cmp_gt_u32_e64 s[42:43], 32, v1
	v_lshl_add_u64 v[180:181], v[2:3], 0, s[8:9]
	v_lshl_add_u64 v[182:183], s[10:11], 0, v[98:99]
	v_lshl_add_u64 v[184:185], s[10:11], 0, v[178:179]
	v_add_u32_e32 v217, v22, v23
	v_add_u32_e32 v218, v6, v7
	v_add_u32_e32 v219, v8, v10
	v_add_u32_e32 v220, v12, v11
	v_add_u32_e32 v221, v24, v20
	v_add_u32_e32 v222, v5, v4
	v_readfirstlane_b32 s1, v194
	s_cmpk_ge_u32 s1, 0x100
	s_cbranch_scc1 .Lmla_prio_skip
	s_setprio 1
